# cross-attention item: gate loads issued one at a time inside the compute section instead of a burst before the second barrier
# speedup vs baseline: 1.0119x; 1.0067x over previous
.LBB0_902:
	s_and_b32 s8, s14, 3
	s_mul_i32 s6, s0, 0x120000
	s_mul_hi_i32 s3, s0, 0x120000
	s_add_u32 s6, s92, s6
	s_addc_u32 s3, s93, s3
	s_lshl_b32 s15, s8, 7
	s_add_u32 s18, s6, s15
	s_addc_u32 s19, s3, 0
	s_ashr_i32 s3, s2, 31
	s_lshl_b64 s[6:7], s[2:3], 17
	s_add_u32 s3, s10, s6
	s_addc_u32 s7, s11, s7
	s_add_u32 s6, s3, s15
	s_addc_u32 s7, s7, 0
	s_lshl_b32 s2, s2, 2
	s_or_b32 s2, s2, s8
	s_ashr_i32 s3, s2, 31
	s_lshl_b64 s[2:3], s[2:3], 15
	s_add_u32 s8, s12, s2
	s_addc_u32 s9, s13, s3
	s_lshl_b64 s[0:1], s[0:1], 19
	s_add_u32 s0, s94, s0
	s_addc_u32 s1, s95, s1
	s_add_u32 s0, s0, s15
	v_mov_b32_e32 v34, v250
	s_addc_u32 s1, s1, 0
	s_add_u32 s2, s18, 0x1000
	v_ashrrev_i32_e32 v0, 1, v34
	v_bfe_u32 v58, v34, 5, 1
	s_waitcnt vmcnt(0)
	v_bfi_b32 v98, s88, v0, v34
	v_mov_b64_e32 v[0:1], s[18:19]
	s_addc_u32 s3, s19, 0
	v_mad_i64_i32 v[0:1], s[18:19], v98, s33, v[0:1]
	v_lshlrev_b32_e32 v176, 4, v58
	v_lshl_add_u64 v[0:1], v[0:1], 0, v[176:177]
	global_load_dwordx4 v[94:97], v[0:1], off offset:3584
	global_load_dwordx4 v[90:93], v[0:1], off offset:3616
	global_load_dwordx4 v[86:89], v[0:1], off offset:3648
	global_load_dwordx4 v[82:85], v[0:1], off offset:3680
	v_ashrrev_i32_e32 v32, 3, v34
	v_lshlrev_b32_e32 v0, 4, v34
	v_and_b32_e32 v4, 0x70, v0
	v_mov_b32_e32 v5, v177
	v_ashrrev_i32_e32 v33, 31, v32
	v_xor_b32_e32 v37, v0, v34
	v_lshl_add_u64 v[0:1], s[6:7], 0, v[4:5]
	v_lshlrev_b64 v[2:3], 9, v[32:33]
	v_lshl_add_u64 v[24:25], v[0:1], 0, v[2:3]
	s_mov_b32 s6, 0x8000
	v_add_co_u32_e32 v8, vcc, s6, v24
	s_mov_b32 s6, 0x10000
	s_nop 0
	v_addc_co_u32_e32 v9, vcc, 0, v25, vcc
	v_lshl_add_u64 v[6:7], s[8:9], 0, v[2:3]
	v_add_co_u32_e32 v16, vcc, s6, v24
	v_lshl_add_u64 v[28:29], v[6:7], 0, v[4:5]
	s_nop 0
	v_addc_co_u32_e32 v17, vcc, 0, v25, vcc
	s_mov_b32 s6, 0x18000
	global_load_dwordx4 v[0:3], v[24:25], off
	global_load_dwordx4 v[4:7], v[28:29], off
	v_add_co_u32_e32 v24, vcc, s6, v24
	global_load_dwordx4 v[8:11], v[8:9], off
	s_nop 0
	global_load_dwordx4 v[12:15], v[28:29], off offset:128
	v_addc_co_u32_e32 v25, vcc, 0, v25, vcc
	global_load_dwordx4 v[16:19], v[16:17], off
	s_nop 0
	global_load_dwordx4 v[20:23], v[28:29], off offset:256
	s_nop 0
	global_load_dwordx4 v[24:27], v[24:25], off
	s_nop 0
	global_load_dwordx4 v[28:31], v[28:29], off offset:384
	v_lshlrev_b32_e32 v32, 7, v32
	s_movk_i32 s6, 0x70
	v_and_or_b32 v32, v37, s6, v32
	s_waitcnt lgkmcnt(0)
	s_barrier
	v_and_b32_e32 v35, 31, v34
	v_lshrrev_b32_e32 v36, 5, v34
	v_bfe_u32 v59, v34, 1, 3
	v_lshlrev_b32_e32 v60, 7, v35
	v_bitop3_b32 v36, v36, v59, 1 bitop3:0x6c
	v_lshl_or_b32 v163, v36, 4, v60
	v_ashrrev_i32_e32 v99, 31, v98
	s_add_i32 s14, s14, s90
	s_cmpk_gt_i32 s14, 0x2ff
	s_waitcnt vmcnt(7)
	ds_write_b128 v32, v[0:3]
	s_waitcnt vmcnt(6)
	ds_write_b128 v32, v[4:7] offset:8192
	s_waitcnt vmcnt(5)
	ds_write_b128 v32, v[8:11] offset:16384
	s_waitcnt vmcnt(4)
	ds_write_b128 v32, v[12:15] offset:24576
	s_waitcnt vmcnt(3)
	ds_write_b128 v32, v[16:19] offset:32768
	s_waitcnt vmcnt(2)
	ds_write_b128 v32, v[20:23] offset:40960
	s_waitcnt vmcnt(1)
	ds_write_b128 v32, v[24:27] offset:49152
	s_waitcnt vmcnt(0)
	ds_write_b128 v32, v[28:31] offset:57344
	v_mov_b64_e32 v[178:179], s[2:3]
	v_mad_i64_i32 v[178:179], s[2:3], v98, s33, v[178:179]
	v_lshl_add_u64 v[178:179], v[178:179], 0, v[176:177]
	v_lshlrev_b32_e32 v1, 1, v34
	v_lshrrev_b32_e32 v2, 1, v34
	v_and_b32_e32 v0, 19, v34
	v_and_b32_e32 v1, 8, v1
	v_and_b32_e32 v2, 4, v2
	v_or3_b32 v0, v1, v0, v2
	v_lshrrev_b32_e32 v37, 1, v0
	v_lshlrev_b32_e32 v38, 7, v0
	v_bitop3_b32 v0, v37, v58, 7 bitop3:0x6c
	v_lshl_or_b32 v103, v0, 4, v38
	s_waitcnt lgkmcnt(0)
	s_barrier
	ds_read_b128 v[0:3], v103
	ds_read_b128 v[16:19], v103 offset:4096
	v_or_b32_e32 v32, 2, v58
	v_bitop3_b32 v32, v37, v32, 7 bitop3:0x6c
	v_lshl_or_b32 v105, v32, 4, v38
	ds_read_b128 v[32:35], v105
	s_waitcnt lgkmcnt(2)
	v_mfma_f32_32x32x16_bf16 v[0:15], v[0:3], v[94:97], 0
	ds_read_b128 v[150:153], v163 offset:12288
	s_mov_b32 s2, 0xf149f2ca
	s_waitcnt lgkmcnt(1)
	v_mfma_f32_32x32x16_bf16 v[0:15], v[32:35], v[90:93], v[0:15]
	ds_read_b128 v[32:35], v105 offset:4096
	v_mfma_f32_32x32x16_bf16 v[16:31], v[16:19], v[94:97], 0
	s_waitcnt lgkmcnt(0)
	v_mfma_f32_32x32x16_bf16 v[16:31], v[32:35], v[90:93], v[16:31]
	v_or_b32_e32 v32, 4, v58
	v_bitop3_b32 v32, v37, v32, 7 bitop3:0x6c
	v_lshl_or_b32 v107, v32, 4, v38
	ds_read_b128 v[32:35], v107
	s_waitcnt lgkmcnt(0)
	v_mfma_f32_32x32x16_bf16 v[0:15], v[32:35], v[86:89], v[0:15]
	ds_read_b128 v[32:35], v107 offset:4096
	s_waitcnt lgkmcnt(0)
	v_mfma_f32_32x32x16_bf16 v[16:31], v[32:35], v[86:89], v[16:31]
	global_load_dwordx4 v[78:81], v[178:179], off
	v_or_b32_e32 v32, 6, v58
	v_bitop3_b32 v32, v37, v32, 7 bitop3:0x6c
	v_lshl_or_b32 v101, v32, 4, v38
	ds_read_b128 v[32:35], v101
	s_waitcnt lgkmcnt(0)
	v_mfma_f32_32x32x16_bf16 v[0:15], v[32:35], v[82:85], v[0:15]
	ds_read_b128 v[32:35], v101 offset:4096
	s_waitcnt lgkmcnt(0)
	v_mfma_f32_32x32x16_bf16 v[16:31], v[32:35], v[82:85], v[16:31]
	s_nop 8
	v_max_f32_e32 v32, v1, v1
	v_max_f32_e32 v33, v0, v0
	v_max_f32_e32 v32, v33, v32
	v_max3_f32 v32, v32, v2, v3
	v_max3_f32 v32, v32, v4, v5
	v_max3_f32 v32, v32, v6, v7
	v_max3_f32 v32, v32, v8, v9
	v_max3_f32 v32, v32, v10, v11
	v_max3_f32 v32, v32, v12, v13
	v_max3_f32 v32, v32, v14, v15
	v_max3_f32 v32, v32, v16, v17
	v_max3_f32 v32, v32, v18, v19
	v_max3_f32 v32, v32, v20, v21
	v_max3_f32 v32, v32, v22, v23
	v_max3_f32 v32, v32, v24, v25
	v_max3_f32 v32, v32, v26, v27
	v_max3_f32 v32, v32, v28, v29
	v_max3_f32 v32, v32, v30, v31
	v_mov_b32_e32 v33, v32
	s_nop 1
	v_permlane32_swap_b32_e32 v32, v33
	v_max3_f32 v109, v32, v33, s2
	v_sub_f32_e32 v0, v0, v109
	v_exp_f32_e32 v38, v0
	v_sub_f32_e32 v0, v16, v109
	v_exp_f32_e32 v39, v0
	v_sub_f32_e32 v37, 0xf149f2ca, v109
	v_add_f32_e32 v0, v38, v39
	v_add_f32_e32 v33, 0, v0
	v_sub_f32_e32 v0, v1, v109
	v_exp_f32_e32 v40, v0
	v_sub_f32_e32 v0, v17, v109
	v_exp_f32_e32 v41, v0
	v_sub_f32_e32 v0, v2, v109
	v_exp_f32_e32 v16, v0
	v_sub_f32_e32 v0, v18, v109
	v_exp_f32_e32 v32, v0
	v_add_f32_e32 v17, v40, v41
	v_cvt_pk_bf16_f32 v62, v38, v40
	v_cvt_pk_bf16_f32 v54, v39, v41
	v_add_f32_e32 v0, v16, v32
	v_add_f32_e32 v1, v17, v33
	s_nop 0
	v_add_f32_e32 v34, v0, v0
	v_add_f32_e32 v35, v0, v1
	v_sub_f32_e32 v0, v3, v109
	v_exp_f32_e32 v17, v0
	v_sub_f32_e32 v0, v19, v109
	v_exp_f32_e32 v33, v0
	v_sub_f32_e32 v0, v4, v109
	v_exp_f32_e32 v18, v0
	v_sub_f32_e32 v0, v20, v109
	v_exp_f32_e32 v34, v0
	v_add_f32_e32 v19, v17, v33
	v_cvt_pk_bf16_f32 v63, v16, v17
	v_cvt_pk_bf16_f32 v55, v32, v33
	v_add_f32_e32 v0, v18, v34
	v_add_f32_e32 v1, v19, v35
	s_nop 0
	v_add_f32_e32 v144, v0, v1
	v_add_f32_e32 v145, v1, v0
	v_sub_f32_e32 v0, v5, v109
	v_exp_f32_e32 v104, v0
	v_sub_f32_e32 v0, v21, v109
	v_exp_f32_e32 v100, v0
	v_sub_f32_e32 v0, v6, v109
	v_exp_f32_e32 v108, v0
	v_sub_f32_e32 v0, v22, v109
	v_exp_f32_e32 v102, v0
	v_sub_f32_e32 v0, v7, v109
	v_exp_f32_e32 v112, v0
	v_sub_f32_e32 v0, v23, v109
	v_exp_f32_e32 v106, v0
	v_sub_f32_e32 v0, v8, v109
	v_exp_f32_e32 v116, v0
	v_sub_f32_e32 v0, v24, v109
	v_exp_f32_e32 v110, v0
	v_sub_f32_e32 v0, v9, v109
	v_exp_f32_e32 v120, v0
	v_sub_f32_e32 v0, v25, v109
	v_exp_f32_e32 v114, v0
	v_sub_f32_e32 v0, v10, v109
	v_exp_f32_e32 v122, v0
	v_sub_f32_e32 v0, v26, v109
	v_exp_f32_e32 v118, v0
	v_sub_f32_e32 v0, v11, v109
	v_exp_f32_e32 v128, v0
	v_sub_f32_e32 v0, v27, v109
	v_exp_f32_e32 v124, v0
	v_sub_f32_e32 v0, v12, v109
	v_exp_f32_e32 v132, v0
	v_sub_f32_e32 v0, v28, v109
	v_exp_f32_e32 v126, v0
	v_sub_f32_e32 v0, v13, v109
	v_exp_f32_e32 v136, v0
	v_sub_f32_e32 v0, v29, v109
	v_exp_f32_e32 v130, v0
	v_sub_f32_e32 v0, v14, v109
	v_exp_f32_e32 v140, v0
	v_sub_f32_e32 v0, v30, v109
	v_exp_f32_e32 v134, v0
	v_sub_f32_e32 v0, v15, v109
	v_exp_f32_e32 v142, v0
	v_sub_f32_e32 v0, v31, v109
	v_exp_f32_e32 v138, v0
	v_exp_f32_e32 v0, v37
	v_cvt_pk_bf16_f32 v56, v34, v100
	ds_read_b128 v[34:37], v163 offset:8192
	v_cvt_pk_bf16_f32 v64, v18, v104
	v_mul_f32_e32 v0, 0, v0
	v_mov_b32_e32 v1, v0
	v_mov_b32_e32 v2, v0
	v_mov_b32_e32 v3, v0
	v_mov_b32_e32 v4, v0
	v_mov_b32_e32 v5, v0
	v_mov_b32_e32 v6, v0
	v_mov_b32_e32 v7, v0
	v_mov_b32_e32 v8, v0
	v_mov_b32_e32 v9, v0
	v_mov_b32_e32 v10, v0
	v_mov_b32_e32 v11, v0
	v_mov_b32_e32 v12, v0
	v_mov_b32_e32 v13, v0
	v_mov_b32_e32 v14, v0
	v_mov_b32_e32 v15, v0
	v_cvt_pk_bf16_f32 v65, v108, v112
	v_cvt_pk_bf16_f32 v146, v116, v120
	v_cvt_pk_bf16_f32 v147, v122, v128
	s_waitcnt lgkmcnt(0)
	v_mfma_f32_32x32x16_bf16 v[18:33], v[34:37], v[62:65], v[0:15]
	v_mov_b64_e32 v[48:49], v[14:15]
	v_mov_b64_e32 v[46:47], v[12:13]
	v_mov_b64_e32 v[44:45], v[10:11]
	v_mov_b64_e32 v[42:43], v[8:9]
	v_mov_b64_e32 v[40:41], v[6:7]
	v_mov_b64_e32 v[38:39], v[4:5]
	v_mov_b64_e32 v[36:37], v[2:3]
	v_mov_b64_e32 v[34:35], v[0:1]
	v_bitop3_b32 v1, v58, v59, 2 bitop3:0x36
	v_lshl_or_b32 v162, v1, 4, v60
	ds_read_b128 v[2:5], v162 offset:8192
	v_cvt_pk_bf16_f32 v148, v132, v136
	v_cvt_pk_bf16_f32 v149, v140, v142
	v_mfma_f32_32x32x16_bf16 v[34:49], v[150:153], v[62:65], v[34:49]
	v_bitop3_b32 v1, v58, v59, 4 bitop3:0x36
	v_lshl_or_b32 v161, v1, 4, v60
	v_cvt_pk_bf16_f32 v57, v102, v106
	v_bitop3_b32 v1, v58, v59, 6 bitop3:0x36
	v_lshl_or_b32 v160, v1, 4, v60
	v_cvt_pk_bf16_f32 v50, v110, v114
	v_cvt_pk_bf16_f32 v51, v118, v124
	s_waitcnt lgkmcnt(0)
	v_mfma_f32_32x32x16_bf16 v[18:33], v[2:5], v[146:149], v[18:33]
	ds_read_b128 v[2:5], v162 offset:12288
	v_cvt_pk_bf16_f32 v52, v126, v130
	v_cvt_pk_bf16_f32 v53, v134, v138
	v_mov_b32_e32 v145, v177
	s_waitcnt lgkmcnt(0)
	v_mfma_f32_32x32x16_bf16 v[34:49], v[2:5], v[146:149], v[34:49]
	ds_read_b128 v[2:5], v161 offset:8192
	ds_read_b128 v[146:149], v105 offset:16384
	s_waitcnt lgkmcnt(1)
	v_mfma_f32_32x32x16_bf16 v[18:33], v[2:5], v[54:57], v[18:33]
	ds_read_b128 v[2:5], v161 offset:12288
	s_waitcnt lgkmcnt(0)
	v_mfma_f32_32x32x16_bf16 v[34:49], v[2:5], v[54:57], v[34:49]
	ds_read_b128 v[2:5], v160 offset:8192
	s_waitcnt lgkmcnt(0)
	v_mfma_f32_32x32x16_bf16 v[18:33], v[2:5], v[50:53], v[18:33]
	ds_read_b128 v[2:5], v160 offset:12288
	s_waitcnt lgkmcnt(0)
	v_mfma_f32_32x32x16_bf16 v[34:49], v[2:5], v[50:53], v[34:49]
	global_load_dwordx4 v[74:77], v[178:179], off offset:32
	ds_read_b128 v[2:5], v103 offset:16384
	ds_read_b128 v[50:53], v103 offset:20480
	s_waitcnt lgkmcnt(1)
	v_mfma_f32_32x32x16_bf16 v[2:17], v[2:5], v[94:97], 0
	v_mfma_f32_32x32x16_bf16 v[2:17], v[146:149], v[90:93], v[2:17]
	ds_read_b128 v[146:149], v105 offset:20480
	s_waitcnt lgkmcnt(1)
	v_mfma_f32_32x32x16_bf16 v[50:65], v[50:53], v[94:97], 0
	s_waitcnt lgkmcnt(0)
	v_mfma_f32_32x32x16_bf16 v[50:65], v[146:149], v[90:93], v[50:65]
	ds_read_b128 v[146:149], v107 offset:16384
	s_waitcnt lgkmcnt(0)
	v_mfma_f32_32x32x16_bf16 v[2:17], v[146:149], v[86:89], v[2:17]
	ds_read_b128 v[146:149], v107 offset:20480
	s_waitcnt lgkmcnt(0)
	v_mfma_f32_32x32x16_bf16 v[50:65], v[146:149], v[86:89], v[50:65]
	ds_read_b128 v[146:149], v101 offset:16384
	s_waitcnt lgkmcnt(0)
	v_mfma_f32_32x32x16_bf16 v[2:17], v[146:149], v[82:85], v[2:17]
	ds_read_b128 v[146:149], v101 offset:20480
	s_waitcnt lgkmcnt(0)
	v_mfma_f32_32x32x16_bf16 v[50:65], v[146:149], v[82:85], v[50:65]
	s_nop 8
	v_max_f32_e32 v1, v3, v3
	v_max_f32_e32 v111, v2, v2
	v_max_f32_e32 v1, v111, v1
	v_max3_f32 v1, v1, v4, v5
	v_max3_f32 v1, v1, v6, v7
	v_max3_f32 v1, v1, v8, v9
	v_max3_f32 v1, v1, v10, v11
	v_max3_f32 v1, v1, v12, v13
	v_max3_f32 v1, v1, v14, v15
	v_max3_f32 v1, v1, v16, v17
	v_max3_f32 v1, v1, v50, v51
	v_max3_f32 v1, v1, v52, v53
	v_max3_f32 v1, v1, v54, v55
	v_max3_f32 v1, v1, v56, v57
	v_max3_f32 v1, v1, v58, v59
	v_max3_f32 v1, v1, v60, v61
	v_max3_f32 v1, v1, v62, v63
	v_max3_f32 v1, v1, v64, v65
	v_mov_b32_e32 v111, v1
	s_nop 1
	v_permlane32_swap_b32_e32 v1, v111
	v_max3_f32 v1, v109, v1, v111
	v_sub_f32_e32 v2, v2, v1
	v_exp_f32_e32 v111, v2
	v_sub_f32_e32 v2, v50, v1
	v_exp_f32_e32 v113, v2
	v_sub_f32_e32 v109, v109, v1
	v_exp_f32_e32 v150, v109
	v_add_f32_e32 v2, v111, v113
	v_add_f32_e32 v153, 0, v2
	v_sub_f32_e32 v2, v3, v1
	v_exp_f32_e32 v115, v2
	v_sub_f32_e32 v2, v51, v1
	v_exp_f32_e32 v117, v2
	v_sub_f32_e32 v2, v4, v1
	v_exp_f32_e32 v50, v2
	v_sub_f32_e32 v2, v52, v1
	v_exp_f32_e32 v152, v2
	v_add_f32_e32 v51, v115, v117
	v_add_f32_e32 v2, v50, v152
	v_add_f32_e32 v3, v51, v153
	s_nop 0
	v_add_f32_e32 v154, v2, v2
	v_add_f32_e32 v155, v2, v3
	v_sub_f32_e32 v2, v5, v1
	v_exp_f32_e32 v51, v2
	v_sub_f32_e32 v2, v53, v1
	v_exp_f32_e32 v119, v2
	v_sub_f32_e32 v2, v6, v1
	v_exp_f32_e32 v52, v2
	v_sub_f32_e32 v2, v54, v1
	v_exp_f32_e32 v154, v2
	v_add_f32_e32 v53, v51, v119
	v_mul_f32_e32 v4, v20, v150
	v_mul_f32_e32 v5, v21, v150
	v_mul_f32_e32 v20, v36, v150
	v_mul_f32_e32 v21, v37, v150
	v_add_f32_e32 v2, v52, v154
	v_add_f32_e32 v3, v53, v155
	s_nop 0
	v_add_f32_e32 v156, v2, v2
	v_add_f32_e32 v157, v2, v3
	v_sub_f32_e32 v2, v7, v1
	v_exp_f32_e32 v53, v2
	v_sub_f32_e32 v2, v55, v1
	v_exp_f32_e32 v121, v2
	v_sub_f32_e32 v2, v8, v1
	v_exp_f32_e32 v54, v2
	v_sub_f32_e32 v2, v56, v1
	v_exp_f32_e32 v156, v2
	v_add_f32_e32 v55, v53, v121
	v_mul_f32_e32 v6, v22, v150
	v_mul_f32_e32 v7, v23, v150
	v_mul_f32_e32 v22, v38, v150
	v_mul_f32_e32 v23, v39, v150
	v_add_f32_e32 v2, v54, v156
	v_add_f32_e32 v3, v55, v157
	v_cvt_pk_bf16_f32 v38, v113, v117
	v_add_f32_e32 v158, v2, v2
	v_add_f32_e32 v159, v2, v3
	v_sub_f32_e32 v2, v9, v1
	v_exp_f32_e32 v55, v2
	v_sub_f32_e32 v2, v57, v1
	v_exp_f32_e32 v123, v2
	v_sub_f32_e32 v2, v10, v1
	v_exp_f32_e32 v56, v2
	v_sub_f32_e32 v2, v58, v1
	v_exp_f32_e32 v158, v2
	v_add_f32_e32 v57, v55, v123
	v_mul_f32_e32 v8, v24, v150
	v_mul_f32_e32 v9, v25, v150
	v_mul_f32_e32 v24, v40, v150
	v_mul_f32_e32 v25, v41, v150
	v_add_f32_e32 v2, v56, v158
	v_add_f32_e32 v3, v57, v159
	v_cvt_pk_bf16_f32 v39, v152, v119
	v_add_f32_e32 v164, v2, v2
	v_add_f32_e32 v165, v2, v3
	v_sub_f32_e32 v2, v11, v1
	v_exp_f32_e32 v57, v2
	v_sub_f32_e32 v2, v59, v1
	v_exp_f32_e32 v125, v2
	v_sub_f32_e32 v2, v12, v1
	v_exp_f32_e32 v58, v2
	v_sub_f32_e32 v2, v60, v1
	v_exp_f32_e32 v164, v2
	v_add_f32_e32 v59, v57, v125
	v_mul_f32_e32 v10, v26, v150
	v_mul_f32_e32 v11, v27, v150
	v_mul_f32_e32 v26, v42, v150
	v_mul_f32_e32 v27, v43, v150
	v_add_f32_e32 v2, v58, v164
	v_add_f32_e32 v3, v59, v165
	v_cvt_pk_bf16_f32 v42, v56, v57
	v_add_f32_e32 v166, v2, v2
	v_add_f32_e32 v167, v2, v3
	v_sub_f32_e32 v2, v13, v1
	v_exp_f32_e32 v59, v2
	v_sub_f32_e32 v2, v61, v1
	v_exp_f32_e32 v127, v2
	v_sub_f32_e32 v2, v14, v1
	v_exp_f32_e32 v60, v2
	v_sub_f32_e32 v2, v62, v1
	v_exp_f32_e32 v166, v2
	v_add_f32_e32 v61, v59, v127
	v_mul_f32_e32 v12, v28, v150
	v_mul_f32_e32 v13, v29, v150
	v_mul_f32_e32 v28, v44, v150
	v_mul_f32_e32 v29, v45, v150
	v_add_f32_e32 v2, v60, v166
	v_add_f32_e32 v3, v61, v167
	v_cvt_pk_bf16_f32 v43, v58, v59
	v_add_f32_e32 v168, v2, v2
	v_add_f32_e32 v169, v2, v3
	v_sub_f32_e32 v2, v15, v1
	v_exp_f32_e32 v61, v2
	v_sub_f32_e32 v2, v63, v1
	v_exp_f32_e32 v129, v2
	v_sub_f32_e32 v2, v16, v1
	v_exp_f32_e32 v62, v2
	v_sub_f32_e32 v2, v64, v1
	v_exp_f32_e32 v168, v2
	v_sub_f32_e32 v2, v17, v1
	v_mul_f32_e32 v16, v32, v150
	v_mul_f32_e32 v17, v33, v150
	v_mul_f32_e32 v14, v30, v150
	v_mul_f32_e32 v15, v31, v150
	v_mul_f32_e32 v32, v48, v150
	v_mul_f32_e32 v33, v49, v150
	v_mul_f32_e32 v30, v46, v150
	v_mul_f32_e32 v31, v47, v150
	v_cvt_pk_bf16_f32 v47, v50, v51
	v_cvt_pk_bf16_f32 v48, v52, v53
	ds_read_b128 v[50:53], v163 offset:24576
	v_add_f32_e32 v63, v61, v129
	v_add_f32_e32 v148, v62, v168
	v_add_f32_e32 v149, v63, v169
	v_exp_f32_e32 v63, v2
	v_sub_f32_e32 v2, v65, v1
	v_exp_f32_e32 v64, v2
	v_mul_f32_e32 v2, v18, v150
	v_mul_f32_e32 v3, v19, v150
	v_cvt_pk_bf16_f32 v46, v111, v115
	v_cvt_pk_bf16_f32 v49, v54, v55
	v_mul_f32_e32 v18, v34, v150
	v_mul_f32_e32 v19, v35, v150
	v_cvt_pk_bf16_f32 v44, v60, v61
	s_waitcnt lgkmcnt(0)
	v_mfma_f32_32x32x16_bf16 v[2:17], v[50:53], v[46:49], v[2:17]
	ds_read_b128 v[50:53], v163 offset:28672
	v_cvt_pk_bf16_f32 v45, v62, v63
	v_cvt_pk_bf16_f32 v40, v154, v121
	v_cvt_pk_bf16_f32 v41, v156, v123
	v_cvt_pk_bf16_f32 v34, v158, v125
	v_cvt_pk_bf16_f32 v35, v164, v127
	v_cvt_pk_bf16_f32 v36, v166, v129
	s_waitcnt lgkmcnt(0)
	v_mfma_f32_32x32x16_bf16 v[18:33], v[50:53], v[46:49], v[18:33]
	global_load_dwordx4 v[70:73], v[178:179], off offset:64
	ds_read_b128 v[46:49], v162 offset:24576
	v_cvt_pk_bf16_f32 v37, v168, v64
	ds_read_b128 v[152:155], v105 offset:32768
	ds_read_b128 v[50:53], v103 offset:36864
	v_add_f32_e32 v146, v63, v64
	s_waitcnt lgkmcnt(2)
	v_mfma_f32_32x32x16_bf16 v[2:17], v[46:49], v[42:45], v[2:17]
	ds_read_b128 v[46:49], v162 offset:28672
	s_waitcnt lgkmcnt(0)
	v_mfma_f32_32x32x16_bf16 v[18:33], v[46:49], v[42:45], v[18:33]
	ds_read_b128 v[42:45], v161 offset:24576
	s_waitcnt lgkmcnt(0)
	v_mfma_f32_32x32x16_bf16 v[2:17], v[42:45], v[38:41], v[2:17]
	ds_read_b128 v[42:45], v161 offset:28672
	s_waitcnt lgkmcnt(0)
	v_mfma_f32_32x32x16_bf16 v[18:33], v[42:45], v[38:41], v[18:33]
	ds_read_b128 v[38:41], v160 offset:24576
	s_waitcnt lgkmcnt(0)
	v_mfma_f32_32x32x16_bf16 v[2:17], v[38:41], v[34:37], v[2:17]
	ds_read_b128 v[38:41], v160 offset:28672
	s_waitcnt lgkmcnt(0)
	v_mfma_f32_32x32x16_bf16 v[18:33], v[38:41], v[34:37], v[18:33]
	ds_read_b128 v[34:37], v103 offset:32768
	s_waitcnt lgkmcnt(0)
	v_mfma_f32_32x32x16_bf16 v[34:49], v[34:37], v[94:97], 0
	v_mfma_f32_32x32x16_bf16 v[34:49], v[152:155], v[90:93], v[34:49]
	ds_read_b128 v[152:155], v105 offset:36864
	v_mfma_f32_32x32x16_bf16 v[50:65], v[50:53], v[94:97], 0
	s_waitcnt lgkmcnt(0)
	v_mfma_f32_32x32x16_bf16 v[50:65], v[152:155], v[90:93], v[50:65]
	global_load_dwordx4 v[66:69], v[178:179], off offset:96
	ds_read_b128 v[152:155], v107 offset:32768
	s_waitcnt lgkmcnt(0)
	v_mfma_f32_32x32x16_bf16 v[34:49], v[152:155], v[86:89], v[34:49]
	ds_read_b128 v[152:155], v107 offset:36864
	s_waitcnt lgkmcnt(0)
	v_mfma_f32_32x32x16_bf16 v[50:65], v[152:155], v[86:89], v[50:65]
	ds_read_b128 v[152:155], v101 offset:32768
	s_waitcnt lgkmcnt(0)
	v_mfma_f32_32x32x16_bf16 v[34:49], v[152:155], v[82:85], v[34:49]
	ds_read_b128 v[152:155], v101 offset:36864
	s_waitcnt lgkmcnt(0)
	v_mfma_f32_32x32x16_bf16 v[50:65], v[152:155], v[82:85], v[50:65]
	s_nop 8
	v_max_f32_e32 v109, v35, v35
	v_max_f32_e32 v111, v34, v34
	v_max_f32_e32 v109, v111, v109
	v_max3_f32 v109, v109, v36, v37
	v_max3_f32 v109, v109, v38, v39
	v_max3_f32 v109, v109, v40, v41
	v_max3_f32 v109, v109, v42, v43
	v_max3_f32 v109, v109, v44, v45
	v_max3_f32 v109, v109, v46, v47
	v_max3_f32 v109, v109, v48, v49
	v_max3_f32 v109, v109, v50, v51
	v_max3_f32 v109, v109, v52, v53
	v_max3_f32 v109, v109, v54, v55
	v_max3_f32 v109, v109, v56, v57
	v_max3_f32 v109, v109, v58, v59
	v_max3_f32 v109, v109, v60, v61
	v_max3_f32 v109, v109, v62, v63
	v_max3_f32 v109, v109, v64, v65
	v_mov_b32_e32 v111, v109
	s_nop 1
	v_permlane32_swap_b32_e32 v109, v111
	v_max3_f32 v109, v1, v109, v111
	v_sub_f32_e32 v34, v34, v109
	v_exp_f32_e32 v111, v34
	v_sub_f32_e32 v34, v50, v109
	v_exp_f32_e32 v113, v34
	v_sub_f32_e32 v1, v1, v109
	v_exp_f32_e32 v156, v1
	v_add_f32_e32 v34, v111, v113
	v_add_f32_e32 v159, 0, v34
	v_sub_f32_e32 v34, v35, v109
	v_exp_f32_e32 v115, v34
	v_sub_f32_e32 v34, v51, v109
	v_exp_f32_e32 v117, v34
	v_sub_f32_e32 v34, v36, v109
	v_sub_f32_e32 v36, v52, v109
	v_exp_f32_e32 v34, v34
	v_exp_f32_e32 v158, v36
	v_add_f32_e32 v35, v115, v117
	v_sub_f32_e32 v36, v53, v109
	v_exp_f32_e32 v119, v36
	v_add_f32_e32 v50, v34, v158
	v_add_f32_e32 v51, v35, v159
	v_sub_f32_e32 v35, v37, v109
	v_add_f32_e32 v51, v50, v51
	v_add_f32_e32 v50, v50, v50
	v_exp_f32_e32 v35, v35
	v_sub_f32_e32 v36, v38, v109
	v_sub_f32_e32 v38, v54, v109
	v_exp_f32_e32 v36, v36
	v_exp_f32_e32 v50, v38
	v_add_f32_e32 v37, v35, v119
	v_sub_f32_e32 v38, v55, v109
	v_mul_f32_e32 v16, v16, v156
	v_mul_f32_e32 v17, v17, v156
	v_add_f32_e32 v52, v36, v50
	v_add_f32_e32 v53, v37, v51
	v_sub_f32_e32 v37, v39, v109
	v_add_f32_e32 v53, v52, v53
	v_add_f32_e32 v52, v52, v52
	v_exp_f32_e32 v37, v37
	v_exp_f32_e32 v51, v38
	v_sub_f32_e32 v38, v40, v109
	v_sub_f32_e32 v40, v56, v109
	v_exp_f32_e32 v38, v38
	v_exp_f32_e32 v52, v40
	v_add_f32_e32 v39, v37, v51
	v_sub_f32_e32 v40, v57, v109
	v_mul_f32_e32 v14, v14, v156
	v_mul_f32_e32 v15, v15, v156
	v_add_f32_e32 v54, v38, v52
	v_add_f32_e32 v55, v39, v53
	v_sub_f32_e32 v39, v41, v109
	v_add_f32_e32 v55, v54, v55
	v_add_f32_e32 v54, v54, v54
	v_exp_f32_e32 v39, v39
	v_exp_f32_e32 v53, v40
	v_sub_f32_e32 v40, v42, v109
	v_sub_f32_e32 v42, v58, v109
	v_exp_f32_e32 v40, v40
	v_exp_f32_e32 v54, v42
	v_add_f32_e32 v41, v39, v53
	v_sub_f32_e32 v42, v59, v109
	v_mul_f32_e32 v12, v12, v156
	v_mul_f32_e32 v13, v13, v156
	v_add_f32_e32 v56, v40, v54
	v_add_f32_e32 v57, v41, v55
	v_sub_f32_e32 v41, v43, v109
	v_exp_f32_e32 v55, v42
	v_sub_f32_e32 v42, v44, v109
	v_add_f32_e32 v57, v56, v57
	v_add_f32_e32 v56, v56, v56
	v_exp_f32_e32 v41, v41
	v_exp_f32_e32 v58, v42
	v_sub_f32_e32 v42, v60, v109
	v_exp_f32_e32 v56, v42
	v_add_f32_e32 v59, v41, v55
	v_mul_f32_e32 v10, v10, v156
	v_mul_f32_e32 v11, v11, v156
	v_mul_f32_e32 v8, v8, v156
	v_mul_f32_e32 v9, v9, v156
	v_add_f32_e32 v42, v58, v56
	v_add_f32_e32 v43, v59, v57
	v_mul_f32_e32 v6, v6, v156
	v_mul_f32_e32 v7, v7, v156
	v_add_f32_e32 v164, v42, v42
	v_add_f32_e32 v165, v42, v43
	v_sub_f32_e32 v42, v45, v109
	v_exp_f32_e32 v57, v42
	v_sub_f32_e32 v42, v61, v109
	v_exp_f32_e32 v59, v42
	v_sub_f32_e32 v42, v46, v109
	v_exp_f32_e32 v44, v42
	v_sub_f32_e32 v42, v62, v109
	v_exp_f32_e32 v164, v42
	v_add_f32_e32 v45, v57, v59
	v_mul_f32_e32 v4, v4, v156
	v_mul_f32_e32 v5, v5, v156
	v_mul_f32_e32 v2, v2, v156
	v_mul_f32_e32 v3, v3, v156
	v_add_f32_e32 v42, v44, v164
	v_add_f32_e32 v43, v45, v165
	v_cvt_pk_bf16_f32 v46, v111, v115
	v_add_f32_e32 v60, v42, v42
	v_add_f32_e32 v61, v42, v43
	v_sub_f32_e32 v42, v47, v109
	v_exp_f32_e32 v45, v42
	v_sub_f32_e32 v42, v63, v109
	v_exp_f32_e32 v121, v42
	v_sub_f32_e32 v42, v48, v109
	v_exp_f32_e32 v62, v42
	v_sub_f32_e32 v42, v64, v109
	v_exp_f32_e32 v60, v42
	v_add_f32_e32 v63, v45, v121
	v_sub_f32_e32 v42, v49, v109
	v_cvt_pk_bf16_f32 v47, v34, v35
	v_add_f32_e32 v154, v62, v60
	v_add_f32_e32 v155, v63, v61
	v_exp_f32_e32 v61, v42
	v_sub_f32_e32 v42, v65, v109
	v_exp_f32_e32 v63, v42
	v_cvt_pk_bf16_f32 v42, v40, v41
	v_cvt_pk_bf16_f32 v40, v50, v51
	v_cvt_pk_bf16_f32 v41, v52, v53
	ds_read_b128 v[50:53], v163 offset:40960
	v_cvt_pk_bf16_f32 v48, v36, v37
	v_cvt_pk_bf16_f32 v49, v38, v39
	v_mul_f32_e32 v32, v32, v156
	v_mul_f32_e32 v33, v33, v156
	v_mul_f32_e32 v30, v30, v156
	v_mul_f32_e32 v31, v31, v156
	s_waitcnt lgkmcnt(0)
	v_mfma_f32_32x32x16_bf16 v[2:17], v[50:53], v[46:49], v[2:17]
	ds_read_b128 v[50:53], v163 offset:45056
	v_mul_f32_e64 v28, v28, v156
	v_mul_f32_e64 v29, v29, v156
	v_mul_f32_e64 v26, v26, v156
	v_mul_f32_e64 v27, v27, v156
	v_mul_f32_e32 v24, v24, v156
	v_mul_f32_e32 v25, v25, v156
	v_mul_f32_e32 v22, v22, v156
	v_mul_f32_e32 v23, v23, v156
	v_mul_f32_e32 v20, v20, v156
	v_mul_f32_e32 v21, v21, v156
	v_mul_f32_e32 v18, v18, v156
	v_mul_f32_e32 v19, v19, v156
	v_cvt_pk_bf16_f32 v43, v58, v57
	v_cvt_pk_bf16_f32 v44, v44, v45
	s_waitcnt lgkmcnt(0)
	v_mfma_f32_32x32x16_bf16 v[18:33], v[50:53], v[46:49], v[18:33]
	ds_read_b128 v[46:49], v162 offset:40960
	v_cvt_pk_bf16_f32 v45, v62, v61
	v_cvt_pk_bf16_f32 v38, v113, v117
	v_cvt_pk_bf16_f32 v39, v158, v119
	v_cvt_pk_bf16_f32 v34, v54, v55
	v_cvt_pk_bf16_f32 v35, v56, v59
	v_cvt_pk_bf16_f32 v36, v164, v121
	s_waitcnt lgkmcnt(0)
	v_mfma_f32_32x32x16_bf16 v[2:17], v[46:49], v[42:45], v[2:17]
	ds_read_b128 v[46:49], v162 offset:45056
	v_cvt_pk_bf16_f32 v37, v60, v63
	ds_read_b128 v[50:53], v103 offset:53248
	v_add_f32_e32 v152, v61, v63
	s_waitcnt lgkmcnt(1)
	v_mfma_f32_32x32x16_bf16 v[18:33], v[46:49], v[42:45], v[18:33]
	ds_read_b128 v[42:45], v161 offset:40960
	s_waitcnt lgkmcnt(0)
	v_mfma_f32_32x32x16_bf16 v[2:17], v[42:45], v[38:41], v[2:17]
	ds_read_b128 v[42:45], v161 offset:45056
	s_waitcnt lgkmcnt(0)
	v_mfma_f32_32x32x16_bf16 v[18:33], v[42:45], v[38:41], v[18:33]
	ds_read_b128 v[38:41], v160 offset:40960
	s_waitcnt lgkmcnt(0)
	v_mfma_f32_32x32x16_bf16 v[2:17], v[38:41], v[34:37], v[2:17]
	ds_read_b128 v[38:41], v160 offset:45056
	s_waitcnt lgkmcnt(0)
	v_mfma_f32_32x32x16_bf16 v[18:33], v[38:41], v[34:37], v[18:33]
	ds_read_b128 v[34:37], v103 offset:49152
	s_waitcnt lgkmcnt(0)
	v_mfma_f32_32x32x16_bf16 v[34:49], v[34:37], v[94:97], 0
	v_mfma_f32_32x32x16_bf16 v[50:65], v[50:53], v[94:97], 0
	ds_read_b128 v[94:97], v105 offset:49152
	s_waitcnt lgkmcnt(0)
	v_mfma_f32_32x32x16_bf16 v[34:49], v[94:97], v[90:93], v[34:49]
	ds_read_b128 v[94:97], v105 offset:53248
	s_waitcnt lgkmcnt(0)
	v_mfma_f32_32x32x16_bf16 v[50:65], v[94:97], v[90:93], v[50:65]
	ds_read_b128 v[90:93], v107 offset:49152
	s_waitcnt lgkmcnt(0)
	v_mfma_f32_32x32x16_bf16 v[34:49], v[90:93], v[86:89], v[34:49]
	ds_read_b128 v[90:93], v107 offset:53248
	s_waitcnt lgkmcnt(0)
	v_mfma_f32_32x32x16_bf16 v[50:65], v[90:93], v[86:89], v[50:65]
	ds_read_b128 v[86:89], v101 offset:49152
	s_waitcnt lgkmcnt(0)
	v_mfma_f32_32x32x16_bf16 v[34:49], v[86:89], v[82:85], v[34:49]
	ds_read_b128 v[86:89], v101 offset:53248
	s_waitcnt lgkmcnt(0)
	v_mfma_f32_32x32x16_bf16 v[50:65], v[86:89], v[82:85], v[50:65]
	s_nop 8
	v_max_f32_e32 v1, v35, v35
	v_max_f32_e32 v82, v34, v34
	v_max_f32_e32 v1, v82, v1
	v_max3_f32 v1, v1, v36, v37
	v_max3_f32 v1, v1, v38, v39
	v_max3_f32 v1, v1, v40, v41
	v_max3_f32 v1, v1, v42, v43
	v_max3_f32 v1, v1, v44, v45
	v_max3_f32 v1, v1, v46, v47
	v_max3_f32 v1, v1, v48, v49
	v_max3_f32 v1, v1, v50, v51
	v_max3_f32 v1, v1, v52, v53
	v_max3_f32 v1, v1, v54, v55
	v_max3_f32 v1, v1, v56, v57
	v_max3_f32 v1, v1, v58, v59
	v_max3_f32 v1, v1, v60, v61
	v_max3_f32 v1, v1, v62, v63
	v_max3_f32 v1, v1, v64, v65
	v_mov_b32_e32 v82, v1
	s_nop 1
	v_permlane32_swap_b32_e32 v1, v82
	v_max3_f32 v82, v109, v1, v82
	v_sub_f32_e32 v1, v34, v82
	v_exp_f32_e32 v105, v1
	v_sub_f32_e32 v1, v50, v82
	v_exp_f32_e32 v101, v1
	v_sub_f32_e32 v1, v35, v82
	v_sub_f32_e32 v83, v109, v82
	v_exp_f32_e32 v109, v1
	v_sub_f32_e32 v1, v51, v82
	v_exp_f32_e32 v103, v1
	v_sub_f32_e32 v1, v36, v82
	v_exp_f32_e32 v113, v1
	v_sub_f32_e32 v1, v52, v82
	v_exp_f32_e32 v107, v1
	v_sub_f32_e32 v1, v37, v82
	v_exp_f32_e32 v117, v1
	v_sub_f32_e32 v1, v53, v82
	v_exp_f32_e32 v111, v1
	v_sub_f32_e32 v1, v38, v82
	v_exp_f32_e32 v121, v1
	v_sub_f32_e32 v1, v54, v82
	v_exp_f32_e32 v115, v1
	v_sub_f32_e32 v1, v39, v82
	v_exp_f32_e32 v123, v1
	v_sub_f32_e32 v1, v55, v82
	v_exp_f32_e32 v119, v1
	v_sub_f32_e32 v1, v40, v82
	v_exp_f32_e32 v129, v1
	v_sub_f32_e32 v1, v56, v82
	v_exp_f32_e32 v125, v1
	v_sub_f32_e32 v1, v41, v82
	v_exp_f32_e32 v133, v1
	v_sub_f32_e32 v1, v57, v82
	v_exp_f32_e32 v127, v1
	v_sub_f32_e32 v1, v42, v82
	v_add_f32_e32 v34, v104, v100
	v_add_f32_e32 v35, v105, v101
	v_exp_f32_e32 v137, v1
	v_sub_f32_e32 v1, v58, v82
	v_add_f32_e32 v34, v34, v144
	v_add_f32_e32 v35, v35, v145
	v_add_f32_e32 v36, v108, v102
	v_add_f32_e32 v37, v109, v103
	v_exp_f32_e32 v131, v1
	v_sub_f32_e32 v1, v43, v82
	v_add_f32_e32 v34, v36, v34
	v_add_f32_e32 v35, v37, v35
	v_add_f32_e32 v36, v112, v106
	v_add_f32_e32 v37, v113, v107
	v_exp_f32_e32 v141, v1
	v_sub_f32_e32 v1, v59, v82
	v_add_f32_e32 v34, v36, v34
	v_add_f32_e32 v35, v37, v35
	v_add_f32_e32 v36, v116, v110
	v_add_f32_e32 v37, v117, v111
	v_exp_f32_e32 v135, v1
	v_sub_f32_e32 v1, v44, v82
	v_add_f32_e32 v34, v36, v34
	v_add_f32_e32 v35, v37, v35
	v_add_f32_e32 v36, v120, v114
	v_add_f32_e32 v37, v121, v115
	v_exp_f32_e32 v143, v1
	v_sub_f32_e32 v1, v60, v82
	v_exp_f32_e32 v139, v1
	v_sub_f32_e32 v1, v45, v82
	v_add_f32_e32 v34, v36, v34
	v_add_f32_e32 v35, v37, v35
	v_add_f32_e32 v36, v122, v118
	v_add_f32_e32 v37, v123, v119
	v_exp_f32_e32 v53, v1
	v_sub_f32_e32 v1, v61, v82
	v_sub_f32_e32 v38, v46, v82
	v_add_f32_e32 v34, v36, v34
	v_add_f32_e32 v35, v37, v35
	v_add_f32_e32 v36, v128, v124
	v_add_f32_e32 v37, v129, v125
	v_exp_f32_e32 v54, v1
	v_exp_f32_e32 v55, v38
	v_sub_f32_e32 v38, v62, v82
	v_add_f32_e32 v34, v36, v34
	v_add_f32_e32 v35, v37, v35
	v_add_f32_e32 v36, v132, v126
	v_add_f32_e32 v37, v133, v127
	v_exp_f32_e32 v56, v38
	v_add_f32_e32 v34, v36, v34
	v_add_f32_e32 v35, v37, v35
	v_add_f32_e32 v36, v136, v130
	v_add_f32_e32 v37, v137, v131
	v_sub_f32_e32 v38, v47, v82
	v_add_f32_e32 v34, v36, v34
	v_add_f32_e32 v35, v37, v35
	v_add_f32_e32 v36, v140, v134
	v_add_f32_e32 v37, v141, v135
	v_exp_f32_e32 v147, v38
	v_sub_f32_e32 v38, v63, v82
	v_add_f32_e32 v34, v36, v34
	v_add_f32_e32 v35, v37, v35
	v_add_f32_e32 v36, v142, v138
	v_add_f32_e32 v37, v143, v139
	v_add_f32_e32 v1, v53, v54
	v_exp_f32_e32 v57, v38
	v_sub_f32_e32 v38, v48, v82
	v_add_f32_e32 v34, v36, v34
	v_add_f32_e32 v35, v37, v35
	v_add_f32_e32 v151, v55, v56
	v_exp_f32_e32 v58, v38
	v_sub_f32_e32 v38, v64, v82
	v_add_f32_e32 v0, v0, v34
	v_add_f32_e32 v1, v1, v35
	v_exp_f32_e32 v59, v38
	v_mul_f32_e32 v34, v0, v150
	v_mul_f32_e32 v35, v1, v151
	v_add_f32_e32 v0, v0, v150
	v_add_f32_e32 v1, v1, v151
	v_sub_f32_e32 v38, v49, v82
	v_mov_b32_e32 v35, v1
	v_add_f32_e32 v0, v148, v149
	v_add_f32_e32 v1, v149, v148
	v_exp_f32_e32 v153, v38
	v_sub_f32_e32 v38, v65, v82
	v_mov_b32_e32 v1, v57
	v_exp_f32_e32 v60, v38
	v_add_f32_e32 v0, v146, v0
	v_add_f32_e32 v1, v147, v1
	v_add_f32_e32 v157, v58, v59
	v_add_f32_e32 v0, v34, v0
	v_add_f32_e32 v1, v35, v1
	v_exp_f32_e32 v52, v83
	v_mul_f32_e32 v34, v0, v156
	v_mul_f32_e32 v35, v1, v157
	v_add_f32_e32 v0, v0, v156
	v_add_f32_e32 v1, v1, v157
	v_mul_f32_e32 v48, v16, v52
	v_mul_f32_e32 v49, v17, v52
	v_mov_b32_e32 v35, v1
	v_add_f32_e32 v0, v154, v155
	v_add_f32_e32 v1, v155, v154
	v_mul_f32_e32 v40, v8, v52
	v_mul_f32_e32 v41, v9, v52
	v_mov_b32_e32 v1, v60
	v_add_f32_e32 v0, v152, v0
	v_add_f32_e32 v1, v153, v1
	v_mul_f32_e32 v8, v26, v52
	v_mul_f32_e32 v9, v27, v52
	v_add_f32_e32 v50, v34, v0
	v_add_f32_e32 v51, v35, v1
	v_mul_f32_e32 v0, v18, v52
	v_mul_f32_e32 v1, v19, v52
	v_cvt_pk_bf16_f32 v26, v55, v147
	v_cvt_pk_bf16_f32 v17, v139, v54
	v_cvt_pk_bf16_f32 v18, v56, v57
	ds_read_b128 v[54:57], v163 offset:57344
	v_mul_f32_e32 v46, v14, v52
	v_mul_f32_e32 v47, v15, v52
	v_mul_f32_e32 v44, v12, v52
	v_mul_f32_e32 v45, v13, v52
	v_mul_f32_e32 v42, v10, v52
	v_mul_f32_e32 v43, v11, v52
	v_mul_f32_e32 v38, v6, v52
	v_mul_f32_e32 v39, v7, v52
	v_mul_f32_e32 v36, v4, v52
	v_mul_f32_e32 v37, v5, v52
	v_mul_f32_e32 v34, v2, v52
	v_mul_f32_e32 v35, v3, v52
	v_mul_f32_e32 v12, v30, v52
	v_mul_f32_e32 v13, v31, v52
	v_mul_f32_e32 v10, v28, v52
	v_mul_f32_e32 v11, v29, v52
	v_cvt_pk_bf16_f32 v28, v105, v109
	v_cvt_pk_bf16_f32 v29, v113, v117
	v_cvt_pk_bf16_f32 v30, v121, v123
	v_cvt_pk_bf16_f32 v31, v129, v133
	v_mul_f32_e32 v14, v32, v52
	v_mul_f32_e32 v15, v33, v52
	v_mul_f32_e32 v6, v24, v52
	v_mul_f32_e32 v7, v25, v52
	s_waitcnt lgkmcnt(0)
	v_mfma_f32_32x32x16_bf16 v[34:49], v[54:57], v[28:31], v[34:49]
	ds_read_b128 v[54:57], v163 offset:61440
	v_mul_f32_e64 v4, v22, v52
	v_mul_f32_e64 v5, v23, v52
	v_mul_f32_e64 v2, v20, v52
	v_mul_f32_e64 v3, v21, v52
	v_cvt_pk_bf16_f32 v24, v137, v141
	v_cvt_pk_bf16_f32 v25, v143, v53
	v_cvt_pk_bf16_f32 v27, v58, v153
	v_cvt_pk_bf16_f32 v20, v101, v103
	s_waitcnt lgkmcnt(0)
	v_mfma_f32_32x32x16_bf16 v[0:15], v[54:57], v[28:31], v[0:15]
	ds_read_b128 v[28:31], v162 offset:57344
	v_cvt_pk_bf16_f32 v21, v107, v111
	v_cvt_pk_bf16_f32 v22, v115, v119
	v_cvt_pk_bf16_f32 v23, v125, v127
	v_cvt_pk_bf16_f32 v16, v131, v135
	v_cvt_pk_bf16_f32 v19, v59, v60
	v_fmac_f32_e32 v51, v50, v52
	s_waitcnt lgkmcnt(0)
	v_mfma_f32_32x32x16_bf16 v[34:49], v[28:31], v[24:27], v[34:49]
	ds_read_b128 v[28:31], v162 offset:61440
	s_waitcnt lgkmcnt(0)
	v_mfma_f32_32x32x16_bf16 v[0:15], v[28:31], v[24:27], v[0:15]
	ds_read_b128 v[24:27], v161 offset:57344
	s_waitcnt lgkmcnt(0)
	v_mfma_f32_32x32x16_bf16 v[34:49], v[24:27], v[20:23], v[34:49]
	ds_read_b128 v[24:27], v161 offset:61440
	s_waitcnt lgkmcnt(0)
	v_mfma_f32_32x32x16_bf16 v[0:15], v[24:27], v[20:23], v[0:15]
	ds_read_b128 v[20:23], v160 offset:57344
	s_waitcnt vmcnt(3)
	v_mov_b32_e32 v26, v81
	s_nop 1
	v_permlane32_swap_b32_e32 v79, v26
	s_waitcnt lgkmcnt(0)
	v_mfma_f32_32x32x16_bf16 v[34:49], v[20:23], v[16:19], v[34:49]
	ds_read_b128 v[20:23], v160 offset:61440
	s_waitcnt lgkmcnt(0)
	v_mfma_f32_32x32x16_bf16 v[0:15], v[20:23], v[16:19], v[0:15]
	v_mov_b32_e32 v16, v51
	s_nop 1
	v_permlane32_swap_b32_e32 v51, v16
	v_add_f32_e32 v16, v51, v16
	v_div_scale_f32 v17, s[2:3], v16, v16, 1.0
	v_rcp_f32_e32 v18, v17
	s_nop 0
	v_fma_f32 v19, -v17, v18, 1.0
	v_fmac_f32_e32 v18, v19, v18
	v_div_scale_f32 v19, vcc, 1.0, v16, 1.0
	v_mul_f32_e32 v20, v19, v18
	v_fma_f32 v21, -v17, v20, v19
	v_fmac_f32_e32 v20, v21, v18
	v_fma_f32 v17, -v17, v20, v19
	v_div_fmas_f32 v17, v17, v18, v20
	v_div_fixup_f32 v20, v17, v16, 1.0
	v_lshlrev_b64 v[16:17], 11, v[98:99]
	v_mov_b32_e32 v21, v80
	v_lshl_add_u64 v[16:17], s[0:1], 0, v[16:17]
	s_nop 0
	v_permlane32_swap_b32_e32 v78, v21
	v_lshl_add_u64 v[22:23], v[16:17], 0, v[176:177]
	v_lshlrev_b32_e32 v16, 16, v78
	v_and_b32_e32 v17, 0xffff0000, v78
	v_mul_f32_e32 v18, v34, v20
	v_mul_f32_e32 v19, v35, v20
	v_mul_f32_e32 v24, v36, v20
	v_mul_f32_e32 v25, v37, v20
	v_mul_f32_e32 v16, v18, v16
	v_mul_f32_e32 v17, v19, v17
	v_lshlrev_b32_e32 v18, 16, v79
	v_and_b32_e32 v19, 0xffff0000, v79
	v_mul_f32_e32 v18, v24, v18
	v_mul_f32_e32 v19, v25, v19
	v_cvt_pk_bf16_f32 v16, v16, v17
	v_cvt_pk_bf16_f32 v17, v18, v19
	v_lshlrev_b32_e32 v18, 16, v21
	v_and_b32_e32 v19, 0xffff0000, v21
	v_mul_f32_e32 v24, v38, v20
	v_mul_f32_e32 v25, v39, v20
	s_nop 0
	v_mul_f32_e32 v18, v24, v18
	v_mul_f32_e32 v19, v25, v19
	v_lshlrev_b32_e32 v24, 16, v26
	v_and_b32_e32 v25, 0xffff0000, v26
	v_mul_f32_e32 v26, v40, v20
	v_mul_f32_e32 v27, v41, v20
	v_cvt_pk_bf16_f32 v18, v18, v19
	v_mul_f32_e32 v24, v26, v24
	v_mul_f32_e32 v25, v27, v25
	s_waitcnt vmcnt(2)
	v_mov_b32_e32 v21, v76
	v_cvt_pk_bf16_f32 v19, v24, v25
	v_permlane32_swap_b32_e32 v16, v18
	s_nop 0
	v_permlane32_swap_b32_e32 v17, v19
	v_permlane32_swap_b32_e32 v74, v21
	v_mov_b32_e32 v26, v77
	global_store_dwordx4 v[22:23], v[16:19], off offset:1536
	s_nop 0
	v_permlane32_swap_b32_e32 v75, v26
	v_lshlrev_b32_e32 v16, 16, v74
	v_and_b32_e32 v17, 0xffff0000, v74
	v_mul_f32_e32 v18, v42, v20
	v_mul_f32_e32 v19, v43, v20
	v_mul_f32_e32 v24, v44, v20
	v_mul_f32_e32 v25, v45, v20
	v_mul_f32_e32 v16, v18, v16
	v_mul_f32_e32 v17, v19, v17
	v_lshlrev_b32_e32 v18, 16, v75
	v_and_b32_e32 v19, 0xffff0000, v75
	v_mul_f32_e32 v18, v24, v18
	v_mul_f32_e32 v19, v25, v19
	v_cvt_pk_bf16_f32 v16, v16, v17
	v_cvt_pk_bf16_f32 v17, v18, v19
	v_lshlrev_b32_e32 v18, 16, v21
	v_and_b32_e32 v19, 0xffff0000, v21
	v_mul_f32_e32 v24, v46, v20
	v_mul_f32_e32 v25, v47, v20
	v_mul_f32_e32 v0, v0, v20
	v_mul_f32_e32 v1, v1, v20
	v_mul_f32_e32 v18, v24, v18
	v_mul_f32_e32 v19, v25, v19
	v_lshlrev_b32_e32 v24, 16, v26
	v_and_b32_e32 v25, 0xffff0000, v26
	v_mul_f32_e32 v26, v48, v20
	v_mul_f32_e32 v27, v49, v20
	v_cvt_pk_bf16_f32 v18, v18, v19
	v_mul_f32_e32 v24, v26, v24
	v_mul_f32_e32 v25, v27, v25
	s_nop 0
	v_permlane32_swap_b32_e32 v16, v18
	v_cvt_pk_bf16_f32 v19, v24, v25
	s_nop 1
	v_permlane32_swap_b32_e32 v17, v19
	global_store_dwordx4 v[22:23], v[16:19], off offset:1568
	v_mul_f32_e32 v2, v2, v20
	v_mul_f32_e32 v3, v3, v20
	v_mul_f32_e32 v4, v4, v20
	v_mul_f32_e32 v5, v5, v20
	s_waitcnt vmcnt(3)
	v_mov_b32_e32 v18, v72
	s_nop 1
	v_permlane32_swap_b32_e32 v70, v18
	v_mov_b32_e32 v19, v73
	s_nop 1
	v_permlane32_swap_b32_e32 v71, v19
	v_lshlrev_b32_e32 v16, 16, v70
	v_and_b32_e32 v17, 0xffff0000, v70
	v_mul_f32_e32 v0, v0, v16
	v_mul_f32_e32 v1, v1, v17
	v_lshlrev_b32_e32 v16, 16, v71
	v_and_b32_e32 v17, 0xffff0000, v71
	v_mul_f32_e32 v2, v2, v16
	v_mul_f32_e32 v3, v3, v17
	v_cvt_pk_bf16_f32 v0, v0, v1
	v_cvt_pk_bf16_f32 v1, v2, v3
	v_lshlrev_b32_e32 v2, 16, v18
	v_and_b32_e32 v3, 0xffff0000, v18
	v_mul_f32_e32 v2, v4, v2
	v_mul_f32_e32 v3, v5, v3
	v_lshlrev_b32_e32 v4, 16, v19
	v_and_b32_e32 v5, 0xffff0000, v19
	v_mul_f32_e32 v6, v6, v20
	v_mul_f32_e32 v7, v7, v20
	v_cvt_pk_bf16_f32 v2, v2, v3
	v_mul_f32_e32 v4, v6, v4
	v_mul_f32_e32 v5, v7, v5
	s_waitcnt vmcnt(2)
	v_mov_b32_e32 v6, v68
	v_cvt_pk_bf16_f32 v3, v4, v5
	v_permlane32_swap_b32_e32 v0, v2
	s_nop 0
	v_permlane32_swap_b32_e32 v1, v3
	v_permlane32_swap_b32_e32 v66, v6
	v_mov_b32_e32 v7, v69
	global_store_dwordx4 v[22:23], v[0:3], off offset:1600
	s_nop 0
	v_permlane32_swap_b32_e32 v67, v7
	v_lshlrev_b32_e32 v0, 16, v66
	v_and_b32_e32 v1, 0xffff0000, v66
	v_mul_f32_e32 v2, v8, v20
	v_mul_f32_e32 v3, v9, v20
	v_mul_f32_e32 v4, v10, v20
	v_mul_f32_e32 v5, v11, v20
	v_mul_f32_e32 v0, v2, v0
	v_mul_f32_e32 v1, v3, v1
	v_lshlrev_b32_e32 v2, 16, v67
	v_and_b32_e32 v3, 0xffff0000, v67
	v_mul_f32_e32 v2, v4, v2
	v_mul_f32_e32 v3, v5, v3
	v_cvt_pk_bf16_f32 v0, v0, v1
	v_cvt_pk_bf16_f32 v1, v2, v3
	v_lshlrev_b32_e32 v2, 16, v6
	v_and_b32_e32 v3, 0xffff0000, v6
	v_mul_f32_e32 v4, v12, v20
	v_mul_f32_e32 v5, v13, v20
	s_nop 0
	v_mul_f32_e32 v2, v4, v2
	v_mul_f32_e32 v3, v5, v3
	v_lshlrev_b32_e32 v4, 16, v7
	v_and_b32_e32 v5, 0xffff0000, v7
	v_mul_f32_e32 v6, v14, v20
	v_mul_f32_e32 v7, v15, v20
	v_cvt_pk_bf16_f32 v2, v2, v3
	v_mul_f32_e32 v4, v6, v4
	v_mul_f32_e32 v5, v7, v5
	s_nop 0
	v_permlane32_swap_b32_e32 v0, v2
	v_cvt_pk_bf16_f32 v3, v4, v5
	s_nop 1
	v_permlane32_swap_b32_e32 v1, v3
	global_store_dwordx4 v[22:23], v[0:3], off offset:1632
	s_cbranch_scc1 .LBB0_907
